# attention main loop: running-max subtraction folded into QK MFMA accumulator init (srcC = -mhat tuple), 66 v_sub removed per 2 steps; outer regs parked in LDS around loop
# baseline (speedup 1.0000x reference)
; #define WAIT_BAR(N) asm volatile("s_waitcnt vmcnt(" #N ") lgkmcnt(0)\n\ts_barrier":::"memory")
;   #define DMA_K(t,slot) glds16(ksrc+(long)(t)*KVBLK*PQ,(unsigned)__builtin_amdgcn_readfirstlane(kdst+(slot)))
;   #define DMA_V(t,slot) glds16(vsrc+(long)(t)*KVBLK*PQ,(unsigned)__builtin_amdgcn_readfirstlane(vdst+(slot)))
;   #define CMASK(P0,P1,t) do{int jb_=(t)-(NT-4); if(jb_>=0)cmask(P0,P1,jb_,qrel,hi);}while(0)
;   #define START(P0,P1) do{ const float rm=rowmax(P0,P1); resc=false; \
;     { const float dl=rm; mhat=fadd_s(mhat,dl); \
;       _Pragma("unroll") for(int r=0;r<16;++r){P0[r]=fsub_s(P0[r],dl);P1[r]=fsub_s(P1[r],dl);} \
;       _Pragma("unroll") for(int r=0;r<16;++r)negm[r]=-mhat; asm volatile("":"+v"(negm)); } \
;     _Pragma("unroll") for(int r=0;r<16;++r)P0[r]=__builtin_amdgcn_exp2f(P0[r]); }while(0)
;   #define ROT() do{sl_prev=sl_cur;sl_cur=sl_next;sl_next=(sl_next==(NSLOT-1)*SLOTB)?0:sl_next+SLOTB;}while(0)
;   #define CMASK(P0,P1,t) do{}while(0)
;   #define CMASK(P0,P1,t) do{int jb_=(t)-(NT-4); if(jb_>=0)cmask(P0,P1,jb_,qrel,hi);}while(0)
; #define WAIT_BAR(N) asm volatile("s_waitcnt vmcnt(" #N ") lgkmcnt(0)\n\ts_barrier":::"memory")
;   #define DMA_K(t,slot) glds16(ksrc+(long)(t)*4096,(unsigned)__builtin_amdgcn_readfirstlane(kdst+(slot)))
;   #define DMA_V(t,slot) do{ glds16(vsrc+(long)(t)*8192,(unsigned)__builtin_amdgcn_readfirstlane(vdst+2*(slot))); glds16(vsrc+(long)(t)*8192+4096,(unsigned)__builtin_amdgcn_readfirstlane(vdst+2*(slot)+8192)); }while(0)
;   #define CMASK(P0,P1,t) do{int jb_=(t)-(NT-4); if(jb_>=0)cmask(P0,P1,jb_,qrel,hi);}while(0)
;   #define ROT() do{sl_prev=sl_cur;sl_cur=sl_next;sl_next=(sl_next==(NSLOT-1)*KSLOT)?0:sl_next+KSLOT;}while(0)
;   #define CMASK(P0,P1,t) do{}while(0)
; template<int THRL> __device__ __forceinline__ void attn_unit128(int qb,const bf16*Qh,const bf16*__restrict__ Kh,const bf16*__restrict__ Vh,bf16*Oh,char*shm){
;     ...
;   float mhat=0.f,l_reg=0.f;f32x16 o[4];o[0]=f32x16{};o[1]=f32x16{};o[2]=f32x16{};o[3]=f32x16{};
;     ...
;   asm volatile("s_nop 15\n\ts_nop 7":"+v"(pA0),"+v"(pA1));CMASK(pA0,pA1,0);
;   START(pA0,pA1);
;   _Pragma("unroll") for(int r=0;r<16;++r)pA1[r]=__builtin_amdgcn_exp2f(pA1[r]);
;   WAIT_BAR(0);
;   DMA_K(3,0);DMA_V(1,KSLOT);
;   ROT();
;   kload8(kf,kp0+sl_cur);
;   WAIT_BAR(3);
;   s16x4 vlo[16],vhi[16]; u32x4 pw0,pw1,pw2,pw3;
.LBB0_367:
	v_lshlrev_b32_e32 v35, 1, v34
	v_lshlrev_b32_e32 v215, 3, v34
	v_lshlrev_b32_e32 v34, 4, v34
	v_and_b32_e32 v218, 32, v35
	v_and_b32_e32 v34, 0xc0, v34
	v_and_b32_e32 v219, 24, v215
	v_lshl_or_b32 v217, v186, 8, v34
	v_add_u32_e32 v34, 0, v218
	v_add3_u32 v224, v34, v219, v217
	v_max3_f32 v34, v0, v1, v16
	v_max3_f32 v35, v2, v3, v17
	s_and_b32 s1, s1, 0x3fffffc0
	v_max3_f32 v34, v34, v18, v19
	v_max3_f32 v35, v35, v6, v7
	s_lshl_b32 s1, s1, 2
	v_max3_f32 v34, v34, v4, v5
	v_max3_f32 v35, v35, v22, v23
	s_add_i32 s34, s1, 0
	v_max3_f32 v34, v34, v20, v21
	v_max3_f32 v35, v35, v10, v11
	s_add_i32 s34, s34, 0x12000
	v_max3_f32 v34, v34, v8, v9
	v_max3_f32 v35, v35, v26, v27
	s_waitcnt vmcnt(0) lgkmcnt(0)
	s_barrier
	s_cmp_lg_u32 0, -1
	v_max3_f32 v34, v34, v24, v25
	v_max3_f32 v35, v35, v14, v15
	s_mov_b32 s72, 1
	v_max3_f32 v34, v34, v12, v13
	v_max3_f32 v35, v35, v30, v31
	s_mov_b32 s28, 0
	v_max3_f32 v34, v34, v28, v29
	v_lshlrev_b32_e32 v225, 4, v186
	v_max_f32_e32 v34, v34, v35
	v_lshl_add_u32 v216, v213, 2, s34
	v_mov_b32_e32 v35, v34
	s_nop 1
	v_permlane32_swap_b32_e32 v34, v35
	v_max_f32_e32 v34, v34, v35
	s_nop 0
	v_sub_f32_e32 v0, v0, v34
	v_sub_f32_e32 v1, v1, v34
	v_sub_f32_e32 v16, v16, v34
	v_sub_f32_e32 v17, v17, v34
	v_sub_f32_e32 v2, v2, v34
	v_sub_f32_e32 v18, v18, v34
	s_nop 0
	v_exp_f32_e32 v80, v0
	v_exp_f32_e32 v81, v1
	v_lshl_add_u64 v[0:1], v[180:181], 0, s[88:89]
	s_mov_b32 s1, m0
	s_mov_b32 m0, s42
	s_nop 0
	global_load_lds_dwordx4 v[0:1], off
	s_mov_b32 m0, s1
	s_cselect_b32 s1, 0, 0
	s_add_i32 s0, s1, s0
	v_lshl_add_u64 v[0:1], v[32:33], 0, s[86:87]
	s_add_i32 s1, s0, 0xa000
	s_mov_b32 s19, m0
	s_mov_b32 m0, s1
	s_nop 0
	global_load_lds_dwordx4 v[0:1], off
	s_mov_b32 m0, s19
	v_lshl_add_u64 v[0:1], v[32:33], 0, s[88:89]
	s_add_i32 s0, s0, 0xc000
	s_mov_b32 s1, m0
	s_mov_b32 m0, s0
	s_nop 0
	global_load_lds_dwordx4 v[0:1], off
	s_mov_b32 m0, s1
	ds_read_b128 v[168:171], v223 offset:8192
	ds_read_b128 v[160:163], v223 offset:8704
	ds_read_b128 v[172:175], v223 offset:10240
	ds_read_b128 v[156:159], v223 offset:10752
	ds_read_b128 v[164:167], v223 offset:12288
	ds_read_b128 v[148:151], v223 offset:12800
	ds_read_b128 v[152:155], v223 offset:14336
	ds_read_b128 v[144:147], v223 offset:14848
	v_sub_f32_e32 v3, v3, v34
	v_sub_f32_e32 v19, v19, v34
	v_sub_f32_e32 v4, v4, v34
	v_sub_f32_e32 v20, v20, v34
	v_sub_f32_e32 v5, v5, v34
	v_sub_f32_e32 v21, v21, v34
	v_sub_f32_e32 v6, v6, v34
	v_sub_f32_e32 v22, v22, v34
	v_sub_f32_e32 v7, v7, v34
	v_sub_f32_e32 v23, v23, v34
	v_sub_f32_e32 v8, v8, v34
	v_sub_f32_e32 v24, v24, v34
	v_sub_f32_e32 v9, v9, v34
	v_sub_f32_e32 v25, v25, v34
	v_sub_f32_e32 v10, v10, v34
	v_sub_f32_e32 v26, v26, v34
	v_sub_f32_e32 v11, v11, v34
	v_sub_f32_e32 v27, v27, v34
	v_sub_f32_e32 v12, v12, v34
	v_sub_f32_e32 v28, v28, v34
	v_sub_f32_e32 v13, v13, v34
	v_sub_f32_e32 v29, v29, v34
	v_sub_f32_e32 v14, v14, v34
	v_sub_f32_e32 v30, v30, v34
	v_sub_f32_e32 v15, v15, v34
	v_sub_f32_e32 v31, v31, v34
	v_exp_f32_e32 v82, v2
	v_exp_f32_e32 v83, v3
	v_exp_f32_e32 v84, v4
	v_exp_f32_e32 v85, v5
	v_exp_f32_e32 v86, v6
	v_exp_f32_e32 v87, v7
	v_exp_f32_e32 v88, v8
	v_exp_f32_e32 v89, v9
	v_exp_f32_e32 v90, v10
	v_exp_f32_e32 v91, v11
	v_exp_f32_e32 v92, v12
	v_exp_f32_e32 v93, v13
	v_exp_f32_e32 v94, v14
	v_exp_f32_e32 v95, v15
	v_exp_f32_e32 v64, v16
	v_exp_f32_e32 v65, v17
	v_exp_f32_e32 v66, v18
	v_exp_f32_e32 v67, v19
	v_exp_f32_e32 v68, v20
	v_exp_f32_e32 v69, v21
	v_exp_f32_e32 v70, v22
	v_exp_f32_e32 v71, v23
	v_exp_f32_e32 v72, v24
	v_exp_f32_e32 v73, v25
	v_exp_f32_e32 v74, v26
	v_exp_f32_e32 v75, v27
	v_exp_f32_e32 v76, v28
	v_exp_f32_e32 v77, v29
	v_exp_f32_e32 v78, v30
	v_exp_f32_e32 v79, v31
	s_waitcnt vmcnt(3) lgkmcnt(0)
	s_barrier
	s_andn2_b64 vcc, exec, s[16:17]
	v_cmp_gt_u32_e64 s[0:1], 32, v212
	v_add_f32_e32 v220, v195, v34
	s_cbranch_vccnz .LBB0_383
	s_add_u32 s20, s59, s24
	s_addc_u32 s21, s60, s25
	v_mov_b32_e32 v32, v195
	v_mov_b32_e32 v33, v195
	v_mov_b32_e32 v46, v195
	v_mov_b32_e32 v47, v195
	v_lshl_add_u64 v[182:183], s[20:21], 0, v[194:195]
	s_mov_b64 s[20:21], 0xa000
	v_mov_b32_e32 v34, v195
	v_mov_b32_e32 v35, v195
	v_mov_b32_e32 v36, v195
	v_mov_b32_e32 v37, v195
	v_mov_b32_e32 v38, v195
	v_mov_b32_e32 v39, v195
	v_mov_b32_e32 v40, v195
	v_mov_b32_e32 v41, v195
	v_mov_b32_e32 v42, v195
	v_mov_b32_e32 v43, v195
	v_mov_b32_e32 v44, v195
	v_mov_b32_e32 v45, v195
	v_mov_b64_e32 v[62:63], v[46:47]
	v_mov_b64_e32 v[16:17], v[32:33]
	v_mov_b64_e32 v[0:1], v[32:33]
	v_lshl_add_u64 v[184:185], v[180:181], 0, s[20:21]
	s_mov_b32 s20, 0
	s_movk_i32 s28, 0x4000
	s_movk_i32 s29, 0x2000
	v_mov_b32_e32 v226, 0
	s_mov_b32 s19, 6
	v_mov_b64_e32 v[60:61], v[44:45]
	v_mov_b64_e32 v[58:59], v[42:43]
	v_mov_b64_e32 v[56:57], v[40:41]
	v_mov_b64_e32 v[54:55], v[38:39]
	v_mov_b64_e32 v[52:53], v[36:37]
	v_mov_b64_e32 v[50:51], v[34:35]
	v_mov_b64_e32 v[48:49], v[32:33]
	v_mov_b64_e32 v[18:19], v[34:35]
	v_mov_b64_e32 v[20:21], v[36:37]
	v_mov_b64_e32 v[22:23], v[38:39]
	v_mov_b64_e32 v[24:25], v[40:41]
	v_mov_b64_e32 v[26:27], v[42:43]
	v_mov_b64_e32 v[28:29], v[44:45]
	v_mov_b64_e32 v[30:31], v[46:47]
	v_mov_b64_e32 v[2:3], v[34:35]
	v_mov_b64_e32 v[4:5], v[36:37]
	v_mov_b64_e32 v[6:7], v[38:39]
	v_mov_b64_e32 v[8:9], v[40:41]
	v_mov_b64_e32 v[10:11], v[42:43]
	v_mov_b64_e32 v[12:13], v[44:45]
	v_mov_b64_e32 v[14:15], v[46:47]
	v_add_u32_e32 v204, 0xfffed800, v222
	v_bfe_u32 v205, v204, 4, 6
	v_lshrrev_b32_e32 v204, 12, v204
	v_cmp_lt_u32_e64 s[98:99], 5, v204
	v_addc_co_u32_e64 v204, s[98:99], 0, v204, s[98:99]
	v_mul_u32_u24_e32 v204, 0xe00, v204
	v_lshl_add_u32 v189, v205, 2, v204
	v_add_u32_e32 v189, 0x1a800, v189
	ds_write_b32 v189, v192
	ds_write_b32 v189, v193 offset:256
	ds_write_b32 v189, v194 offset:512
	ds_write_b32 v189, v195 offset:768
	ds_write_b32 v189, v196 offset:1024
	ds_write_b32 v189, v197 offset:1280
	ds_write_b32 v189, v198 offset:1536
	ds_write_b32 v189, v199 offset:1792
	ds_write_b32 v189, v200 offset:2048
	ds_write_b32 v189, v201 offset:2304
	ds_write_b32 v189, v202 offset:2560
	ds_write_b32 v189, v203 offset:2816
	ds_write_b32 v189, v206 offset:3072
	ds_write_b32 v189, v207 offset:3328
	s_waitcnt lgkmcnt(0)
	v_sub_f32_e32 v192, 0, v220
	v_sub_f32_e32 v193, 0, v220
	v_sub_f32_e32 v194, 0, v220
	v_sub_f32_e32 v195, 0, v220
	v_sub_f32_e32 v196, 0, v220
	v_sub_f32_e32 v197, 0, v220
	v_sub_f32_e32 v198, 0, v220
	v_sub_f32_e32 v199, 0, v220
	v_sub_f32_e32 v200, 0, v220
	v_sub_f32_e32 v201, 0, v220
	v_sub_f32_e32 v202, 0, v220
	v_sub_f32_e32 v203, 0, v220
	v_sub_f32_e32 v204, 0, v220
	v_sub_f32_e32 v205, 0, v220
	v_sub_f32_e32 v206, 0, v220
	v_sub_f32_e32 v207, 0, v220
.LBB0_369:
	s_lshl_b32 s20, s20, 1
	v_add_u32_e32 v187, s20, v224
	ds_read_b128 v[96:99], v222
	ds_read_b128 v[228:231], v222 offset:1024
	ds_read_b128 v[232:235], v222 offset:2048
	ds_read_b128 v[248:251], v222 offset:3072
	ds_read_b64_tr_b16 v[176:177], v187 offset:24576
	ds_read_b64_tr_b16 v[178:179], v187 offset:25088
	s_waitcnt lgkmcnt(5)
	v_mfma_f32_32x32x16_bf16 v[112:127], v[168:171], v[96:99], v[192:207]
	v_add_f32_e32 v100, v80, v81
	v_add_f32_e32 v100, v82, v100
	v_add_f32_e32 v100, v83, v100
	v_add_f32_e32 v100, v84, v100
	v_add_f32_e32 v100, v85, v100
	v_cvt_pk_bf16_f32 v140, v80, v81
	v_cvt_pk_bf16_f32 v141, v82, v83
	ds_read_b64_tr_b16 v[168:169], v187 offset:28672
	ds_read_b64_tr_b16 v[170:171], v187 offset:29184
	v_add_f32_e32 v80, v86, v100
	v_mfma_f32_32x32x16_bf16 v[96:111], v[160:163], v[96:99], v[192:207]
	v_add_f32_e32 v80, v87, v80
	v_add_f32_e32 v80, v88, v80
	v_add_f32_e32 v80, v89, v80
	v_cvt_pk_bf16_f32 v142, v84, v85
	v_cvt_pk_bf16_f32 v143, v86, v87
	ds_read_b64_tr_b16 v[84:85], v187 offset:32768
	ds_read_b64_tr_b16 v[86:87], v187 offset:33280
	s_waitcnt lgkmcnt(8)
	v_mfma_f32_32x32x16_bf16 v[112:127], v[172:175], v[228:231], v[112:127]
	v_add_f32_e32 v80, v90, v80
	v_add_f32_e32 v80, v91, v80
	v_add_f32_e32 v80, v92, v80
	v_add_f32_e32 v128, v93, v80
	v_cvt_pk_bf16_f32 v136, v88, v89
	v_cvt_pk_bf16_f32 v137, v90, v91
	ds_read_b64_tr_b16 v[80:81], v187 offset:36864
	ds_read_b64_tr_b16 v[82:83], v187 offset:37376
	v_mfma_f32_32x32x16_bf16 v[96:111], v[156:159], v[228:231], v[96:111]
	v_add_f32_e32 v88, v94, v128
	v_add_f32_e32 v88, v95, v88
	v_add_f32_e32 v88, v64, v88
	v_add_f32_e32 v88, v65, v88
	v_cvt_pk_bf16_f32 v138, v92, v93
	v_cvt_pk_bf16_f32 v139, v94, v95
	ds_read_b64_tr_b16 v[92:93], v187 offset:25600
	ds_read_b64_tr_b16 v[94:95], v187 offset:26112
	s_waitcnt lgkmcnt(11)
	v_mfma_f32_32x32x16_bf16 v[112:127], v[164:167], v[232:235], v[112:127]
	v_add_f32_e32 v88, v66, v88
	v_add_f32_e32 v88, v67, v88
	v_add_f32_e32 v88, v68, v88
	v_add_f32_e32 v128, v69, v88
	v_cvt_pk_bf16_f32 v132, v64, v65
	v_cvt_pk_bf16_f32 v133, v66, v67
	ds_read_b64_tr_b16 v[88:89], v187 offset:29696
	ds_read_b64_tr_b16 v[90:91], v187 offset:30208
	v_mfma_f32_32x32x16_bf16 v[96:111], v[148:151], v[232:235], v[96:111]
	v_add_f32_e32 v64, v70, v128
	v_add_f32_e32 v64, v71, v64
	v_add_f32_e32 v64, v72, v64
	v_add_f32_e32 v64, v73, v64
	v_cvt_pk_bf16_f32 v134, v68, v69
	v_cvt_pk_bf16_f32 v135, v70, v71
	ds_read_b64_tr_b16 v[68:69], v187 offset:33792
	ds_read_b64_tr_b16 v[70:71], v187 offset:34304
	s_waitcnt lgkmcnt(14)
	v_mfma_f32_32x32x16_bf16 v[112:127], v[152:155], v[248:251], v[112:127]
	v_add_f32_e32 v64, v74, v64
	v_add_f32_e32 v64, v75, v64
	v_add_f32_e32 v64, v76, v64
	v_add_f32_e32 v148, v77, v64
	v_cvt_pk_bf16_f32 v128, v72, v73
	v_cvt_pk_bf16_f32 v129, v74, v75
	ds_read_b64_tr_b16 v[64:65], v187 offset:37888
	ds_read_b64_tr_b16 v[66:67], v187 offset:38400
	v_mfma_f32_32x32x16_bf16 v[96:111], v[144:147], v[248:251], v[96:111]
	v_add_f32_e32 v72, v78, v148
	v_add_f32_e32 v72, v79, v72
	v_add_f32_e32 v74, 0, v72
	v_cvt_pk_bf16_f32 v130, v76, v77
	v_cvt_pk_bf16_f32 v131, v78, v79
	v_lshl_add_u64 v[72:73], v[184:185], 0, s[90:91]
	s_add_i32 s20, s29, s42
	s_mov_b32 s21, m0
	s_mov_b32 m0, s20
	s_nop 0
	global_load_lds_dwordx4 v[72:73], off
	s_mov_b32 m0, s21
	s_movk_i32 s20, 0xc000
	s_mov_b32 s21, -1
	v_lshl_add_u64 v[72:73], v[182:183], 0, s[20:21]
	s_lshl_b32 s20, s28, 1
	s_add_i32 s20, s20, s43
	s_mov_b32 s21, m0
	s_mov_b32 m0, s20
	s_nop 0
	global_load_lds_dwordx4 v[72:73], off
	s_mov_b32 m0, s21
	v_lshl_add_u64 v[72:73], v[182:183], 0, s[90:91]
	s_addk_i32 s20, 0x2000
	s_mov_b32 s21, m0
	s_mov_b32 m0, s20
	s_nop 0
	global_load_lds_dwordx4 v[72:73], off
	s_mov_b32 m0, s21
	v_max_f32_e32 v72, v113, v113
	v_max_f32_e32 v73, v112, v112
	v_max_f32_e32 v72, v73, v72
	v_max3_f32 v73, v114, v115, v97
	v_max3_f32 v72, v72, v96, v98
	v_max3_f32 v72, v72, v99, v116
	v_max3_f32 v73, v73, v118, v119
	v_max3_f32 v72, v72, v117, v100
	v_max3_f32 v73, v73, v102, v103
	v_max3_f32 v72, v72, v101, v120
	v_max3_f32 v73, v73, v122, v123
	v_max3_f32 v72, v72, v121, v104
	v_max3_f32 v73, v73, v106, v107
	v_max3_f32 v72, v72, v105, v124
	v_max3_f32 v73, v73, v126, v127
	v_max3_f32 v72, v72, v125, v108
	v_max3_f32 v73, v73, v110, v111
	v_max3_f32 v72, v72, v109, v73
	v_mov_b32_e32 v73, v72
	s_nop 1
	v_permlane32_swap_b32_e32 v72, v73
	v_max_f32_e32 v73, v73, v73
	v_max_f32_e32 v72, v72, v72
	v_max_f32_e32 v72, v72, v73
	v_cmp_lt_f32_e32 vcc, s92, v72
	s_cmp_lg_u64 vcc, 0
	v_add_f32_e32 v190, v226, v74
	s_cselect_b64 s[20:21], -1, 0
	s_cbranch_vccnz .LBB0_377
.LBB0_370:
	s_waitcnt lgkmcnt(14)
	v_mfma_f32_32x32x16_bf16 v[32:47], v[140:143], v[176:179], v[32:47]
	v_exp_f32_e32 v112, v112
	v_exp_f32_e32 v113, v113
	ds_read_b64_tr_b16 v[72:73], v187 offset:26624
	ds_read_b64_tr_b16 v[74:75], v187 offset:27136
	s_waitcnt lgkmcnt(14)
	v_mfma_f32_32x32x16_bf16 v[48:63], v[140:143], v[168:171], v[48:63]
	v_exp_f32_e32 v114, v114
	v_exp_f32_e32 v115, v115
	ds_read_b64_tr_b16 v[76:77], v187 offset:30720
	ds_read_b64_tr_b16 v[78:79], v187 offset:31232
	s_waitcnt lgkmcnt(14)
	v_mfma_f32_32x32x16_bf16 v[16:31], v[140:143], v[84:87], v[16:31]
	v_exp_f32_e32 v116, v116
	v_exp_f32_e32 v117, v117
	ds_read_b64_tr_b16 v[84:85], v187 offset:34816
	ds_read_b64_tr_b16 v[86:87], v187 offset:35328
	s_waitcnt lgkmcnt(14)
	v_mfma_f32_32x32x16_bf16 v[0:15], v[140:143], v[80:83], v[0:15]
	v_exp_f32_e32 v118, v118
	v_exp_f32_e32 v119, v119
	ds_read_b64_tr_b16 v[80:81], v187 offset:38912
	ds_read_b64_tr_b16 v[82:83], v187 offset:39424
	s_waitcnt lgkmcnt(14)
	v_mfma_f32_32x32x16_bf16 v[32:47], v[136:139], v[92:95], v[32:47]
	v_exp_f32_e32 v120, v120
	v_exp_f32_e32 v121, v121
	ds_read_b64_tr_b16 v[92:93], v187 offset:27648
	ds_read_b64_tr_b16 v[94:95], v187 offset:28160
	s_waitcnt lgkmcnt(14)
	v_mfma_f32_32x32x16_bf16 v[48:63], v[136:139], v[88:91], v[48:63]
	v_exp_f32_e32 v122, v122
	v_exp_f32_e32 v123, v123
	ds_read_b64_tr_b16 v[88:89], v187 offset:31744
	ds_read_b64_tr_b16 v[90:91], v187 offset:32256
	s_waitcnt lgkmcnt(14)
	v_mfma_f32_32x32x16_bf16 v[16:31], v[136:139], v[68:71], v[16:31]
	v_exp_f32_e32 v124, v124
	v_exp_f32_e32 v125, v125
	ds_read_b64_tr_b16 v[168:169], v187 offset:35840
	ds_read_b64_tr_b16 v[170:171], v187 offset:36352
	s_waitcnt lgkmcnt(14)
	v_mfma_f32_32x32x16_bf16 v[0:15], v[136:139], v[64:67], v[0:15]
	v_exp_f32_e32 v126, v126
	v_exp_f32_e32 v127, v127
	ds_read_b64_tr_b16 v[172:173], v187 offset:39936
	ds_read_b64_tr_b16 v[174:175], v187 offset:40448
	v_add_u32_e32 v136, s28, v223
	ds_read_b128 v[68:71], v136
	ds_read_b128 v[64:67], v136 offset:512
	s_waitcnt lgkmcnt(14)
	v_mfma_f32_32x32x16_bf16 v[32:47], v[132:135], v[72:75], v[32:47]
	v_exp_f32_e32 v96, v96
	v_exp_f32_e32 v97, v97
	v_mfma_f32_32x32x16_bf16 v[48:63], v[132:135], v[76:79], v[48:63]
	v_exp_f32_e32 v98, v98
	v_exp_f32_e32 v99, v99
	ds_read_b128 v[164:167], v136 offset:2048
	ds_read_b128 v[152:155], v136 offset:2560
	s_waitcnt lgkmcnt(14)
	v_mfma_f32_32x32x16_bf16 v[16:31], v[132:135], v[84:87], v[16:31]
	v_exp_f32_e32 v100, v100
	v_exp_f32_e32 v101, v101
	s_waitcnt lgkmcnt(12)
	v_mfma_f32_32x32x16_bf16 v[0:15], v[132:135], v[80:83], v[0:15]
	v_exp_f32_e32 v102, v102
	v_exp_f32_e32 v103, v103
	ds_read_b128 v[160:163], v136 offset:4096
	ds_read_b128 v[148:151], v136 offset:4608
	s_waitcnt lgkmcnt(12)
	v_mfma_f32_32x32x16_bf16 v[32:47], v[128:131], v[92:95], v[32:47]
	v_exp_f32_e32 v104, v104
	v_exp_f32_e32 v105, v105
	s_waitcnt lgkmcnt(10)
	v_mfma_f32_32x32x16_bf16 v[48:63], v[128:131], v[88:91], v[48:63]
	v_exp_f32_e32 v106, v106
	v_exp_f32_e32 v107, v107
	ds_read_b128 v[156:159], v136 offset:6144
	ds_read_b128 v[144:147], v136 offset:6656
	s_waitcnt lgkmcnt(10)
	v_mfma_f32_32x32x16_bf16 v[16:31], v[128:131], v[168:171], v[16:31]
	v_exp_f32_e32 v108, v108
	v_exp_f32_e32 v109, v109
	s_waitcnt lgkmcnt(8)
	v_mfma_f32_32x32x16_bf16 v[0:15], v[128:131], v[172:175], v[0:15]
	v_exp_f32_e32 v110, v110
	v_exp_f32_e32 v111, v111
	s_waitcnt vmcnt(3) lgkmcnt(0)
	s_barrier
	s_andn2_b64 vcc, exec, s[20:21]
	v_add_u32_e32 v187, s34, v225
	s_cbranch_vccnz .LBB0_372
	s_waitcnt lgkmcnt(0)
	ds_read_b128 v[72:75], v187 offset:96
	ds_read_b128 v[76:79], v187 offset:64
	ds_read_b128 v[80:83], v187 offset:32
	ds_read_b128 v[84:87], v187
	s_waitcnt lgkmcnt(3)
	v_pk_mul_f32 v[44:45], v[44:45], v[72:73]
	s_waitcnt lgkmcnt(2)
	v_pk_mul_f32 v[40:41], v[40:41], v[76:77]
	s_waitcnt lgkmcnt(1)
	v_pk_mul_f32 v[36:37], v[36:37], v[80:81]
	v_pk_mul_f32 v[46:47], v[46:47], v[74:75]
	v_pk_mul_f32 v[42:43], v[42:43], v[78:79]
	v_pk_mul_f32 v[38:39], v[38:39], v[82:83]
	s_waitcnt lgkmcnt(0)
	v_pk_mul_f32 v[34:35], v[34:35], v[86:87]
	v_pk_mul_f32 v[32:33], v[32:33], v[84:85]
	v_pk_mul_f32 v[60:61], v[60:61], v[72:73]
	v_pk_mul_f32 v[56:57], v[56:57], v[76:77]
	v_pk_mul_f32 v[52:53], v[52:53], v[80:81]
	v_pk_mul_f32 v[62:63], v[62:63], v[74:75]
	v_pk_mul_f32 v[58:59], v[58:59], v[78:79]
	v_pk_mul_f32 v[54:55], v[54:55], v[82:83]
	v_pk_mul_f32 v[50:51], v[50:51], v[86:87]
	v_pk_mul_f32 v[48:49], v[48:49], v[84:85]
	v_pk_mul_f32 v[28:29], v[28:29], v[72:73]
	v_pk_mul_f32 v[24:25], v[24:25], v[76:77]
	v_pk_mul_f32 v[20:21], v[20:21], v[80:81]
	v_pk_mul_f32 v[30:31], v[30:31], v[74:75]
	v_pk_mul_f32 v[26:27], v[26:27], v[78:79]
	v_pk_mul_f32 v[22:23], v[22:23], v[82:83]
	v_pk_mul_f32 v[18:19], v[18:19], v[86:87]
	v_pk_mul_f32 v[16:17], v[16:17], v[84:85]
	v_pk_mul_f32 v[12:13], v[12:13], v[72:73]
	v_pk_mul_f32 v[8:9], v[8:9], v[76:77]
	v_pk_mul_f32 v[4:5], v[4:5], v[80:81]
	v_pk_mul_f32 v[14:15], v[14:15], v[74:75]
	v_pk_mul_f32 v[10:11], v[10:11], v[78:79]
	v_pk_mul_f32 v[6:7], v[6:7], v[82:83]
	v_pk_mul_f32 v[2:3], v[2:3], v[86:87]
	v_pk_mul_f32 v[0:1], v[0:1], v[84:85]
.LBB0_372:
	s_add_i32 s20, s28, 0x2000
	s_cmpk_lg_i32 s28, 0x4000
	s_cselect_b32 s97, s20, 0
	s_lshl_b32 s20, s29, 1
	v_add_u32_e32 v191, s20, v224
	ds_read_b128 v[72:75], v222
	ds_read_b128 v[226:229], v222 offset:1024
	ds_read_b128 v[230:233], v222 offset:2048
	ds_read_b128 v[234:237], v222 offset:3072
	ds_read_b64_tr_b16 v[176:177], v191 offset:24576
	ds_read_b64_tr_b16 v[178:179], v191 offset:25088
	s_waitcnt lgkmcnt(5)
	v_mfma_f32_32x32x16_bf16 v[80:95], v[68:71], v[72:75], v[192:207]
	v_add_f32_e32 v76, v112, v113
	v_add_f32_e32 v76, v114, v76
	v_add_f32_e32 v76, v115, v76
	v_add_f32_e32 v76, v116, v76
	v_add_f32_e32 v76, v117, v76
	v_cvt_pk_bf16_f32 v140, v112, v113
	v_cvt_pk_bf16_f32 v141, v114, v115
	ds_read_b64_tr_b16 v[172:173], v191 offset:28672
	ds_read_b64_tr_b16 v[174:175], v191 offset:29184
	v_add_f32_e32 v68, v118, v76
	v_add_f32_e32 v68, v119, v68
	v_add_f32_e32 v68, v120, v68
	v_add_f32_e32 v112, v121, v68
	v_mfma_f32_32x32x16_bf16 v[64:79], v[64:67], v[72:75], v[192:207]
	v_cvt_pk_bf16_f32 v142, v116, v117
	v_cvt_pk_bf16_f32 v143, v118, v119
	ds_read_b64_tr_b16 v[168:169], v191 offset:32768
	ds_read_b64_tr_b16 v[170:171], v191 offset:33280
	s_waitcnt lgkmcnt(8)
	v_mfma_f32_32x32x16_bf16 v[80:95], v[164:167], v[226:229], v[80:95]
	v_add_f32_e32 v112, v122, v112
	v_add_f32_e32 v112, v123, v112
	v_add_f32_e32 v112, v124, v112
	v_add_f32_e32 v112, v125, v112
	v_cvt_pk_bf16_f32 v136, v120, v121
	v_cvt_pk_bf16_f32 v137, v122, v123
	ds_read_b64_tr_b16 v[120:121], v191 offset:36864
	ds_read_b64_tr_b16 v[122:123], v191 offset:37376
	v_mfma_f32_32x32x16_bf16 v[64:79], v[152:155], v[226:229], v[64:79]
	v_add_f32_e32 v112, v126, v112
	v_add_f32_e32 v112, v127, v112
	v_add_f32_e32 v112, v96, v112
	v_add_f32_e32 v112, v97, v112
	v_cvt_pk_bf16_f32 v138, v124, v125
	v_cvt_pk_bf16_f32 v139, v126, v127
	ds_read_b64_tr_b16 v[116:117], v191 offset:25600
	ds_read_b64_tr_b16 v[118:119], v191 offset:26112
	s_waitcnt lgkmcnt(11)
	v_mfma_f32_32x32x16_bf16 v[80:95], v[160:163], v[230:233], v[80:95]
	v_add_f32_e32 v112, v98, v112
	v_add_f32_e32 v112, v99, v112
	v_add_f32_e32 v112, v100, v112
	v_add_f32_e32 v124, v101, v112
	v_cvt_pk_bf16_f32 v132, v96, v97
	v_cvt_pk_bf16_f32 v133, v98, v99
	ds_read_b64_tr_b16 v[112:113], v191 offset:29696
	ds_read_b64_tr_b16 v[114:115], v191 offset:30208
	v_mfma_f32_32x32x16_bf16 v[64:79], v[148:151], v[230:233], v[64:79]
	v_add_f32_e32 v96, v102, v124
	v_add_f32_e32 v96, v103, v96
	v_add_f32_e32 v96, v104, v96
	v_add_f32_e32 v96, v105, v96
	v_cvt_pk_bf16_f32 v134, v100, v101
	v_cvt_pk_bf16_f32 v135, v102, v103
	ds_read_b64_tr_b16 v[100:101], v191 offset:33792
	ds_read_b64_tr_b16 v[102:103], v191 offset:34304
	s_waitcnt lgkmcnt(14)
	v_mfma_f32_32x32x16_bf16 v[80:95], v[156:159], v[234:237], v[80:95]
	v_add_f32_e32 v96, v106, v96
	v_add_f32_e32 v96, v107, v96
	v_add_f32_e32 v96, v108, v96
	v_add_f32_e32 v124, v109, v96
	v_cvt_pk_bf16_f32 v128, v104, v105
	v_cvt_pk_bf16_f32 v129, v106, v107
	ds_read_b64_tr_b16 v[96:97], v191 offset:37888
	ds_read_b64_tr_b16 v[98:99], v191 offset:38400
	v_mfma_f32_32x32x16_bf16 v[64:79], v[144:147], v[234:237], v[64:79]
	v_add_f32_e32 v104, v110, v124
	v_add_f32_e32 v104, v111, v104
	v_add_f32_e32 v106, 0, v104
	v_cvt_pk_bf16_f32 v130, v108, v109
	v_cvt_pk_bf16_f32 v131, v110, v111
	s_add_i32 s20, s28, s42
	s_mov_b32 s21, m0
	s_mov_b32 m0, s20
	s_nop 0
	global_load_lds_dwordx4 v[184:185], off
	s_mov_b32 m0, s21
	s_lshl_b32 s20, s97, 1
	s_add_i32 s20, s20, s43
	s_mov_b32 s21, m0
	s_mov_b32 m0, s20
	s_nop 0
	global_load_lds_dwordx4 v[182:183], off
	s_mov_b32 m0, s21
	v_lshl_add_u64 v[104:105], v[182:183], 0, s[84:85]
	s_addk_i32 s20, 0x2000
	s_mov_b32 s21, m0
	s_mov_b32 m0, s20
	s_nop 0
	global_load_lds_dwordx4 v[104:105], off
	s_mov_b32 m0, s21
	v_max_f32_e32 v104, v81, v81
	v_max_f32_e32 v105, v80, v80
	v_max_f32_e32 v104, v105, v104
	v_max3_f32 v105, v82, v83, v65
	v_max3_f32 v104, v104, v64, v66
	v_max3_f32 v104, v104, v67, v84
	v_max3_f32 v105, v105, v86, v87
	v_max3_f32 v104, v104, v85, v68
	v_max3_f32 v105, v105, v70, v71
	v_max3_f32 v104, v104, v69, v88
	v_max3_f32 v105, v105, v90, v91
	v_max3_f32 v104, v104, v89, v72
	v_max3_f32 v105, v105, v74, v75
	v_max3_f32 v104, v104, v73, v92
	v_max3_f32 v105, v105, v94, v95
	v_max3_f32 v104, v104, v93, v76
	v_max3_f32 v105, v105, v78, v79
	v_max3_f32 v104, v104, v77, v105
	v_mov_b32_e32 v105, v104
	s_nop 1
	v_permlane32_swap_b32_e32 v104, v105
	v_max_f32_e32 v105, v105, v105
	v_max_f32_e32 v104, v104, v104
	v_max_f32_e32 v104, v104, v105
	v_cmp_lt_f32_e32 vcc, s92, v104
	s_cmp_lg_u64 vcc, 0
	v_add_f32_e32 v226, v190, v106
	s_cselect_b64 s[20:21], -1, 0
	s_cbranch_vccnz .LBB0_380
; #define WAIT_BAR(N) asm volatile("s_waitcnt vmcnt(" #N ") lgkmcnt(0)\n\ts_barrier":::"memory")
;   #define RESC() do{ if(resc){ asm volatile("s_waitcnt lgkmcnt(0)":::"memory"); \
;       _Pragma("unroll") for(int d_=0;d_<2;++d_) _Pragma("unroll") for(int r=0;r<16;++r)o[d_][r]*=wsf[crow(r,hi)]; } }while(0)
;   #define ROT() do{sl_prev=sl_cur;sl_cur=sl_next;sl_next=(sl_next==(NSLOT-1)*SLOTB)?0:sl_next+SLOTB;}while(0)
; #define WAIT_BAR(N) asm volatile("s_waitcnt vmcnt(" #N ") lgkmcnt(0)\n\ts_barrier":::"memory")
;   #define RESC() do{ if(resc){ asm volatile("s_waitcnt lgkmcnt(0)":::"memory"); \
;       _Pragma("unroll") for(int d_=0;d_<4;++d_) _Pragma("unroll") for(int r=0;r<16;++r)o[d_][r]*=wsf[crow(r,hi)]; } }while(0)
;   #define ROT() do{sl_prev=sl_cur;sl_cur=sl_next;sl_next=(sl_next==(NSLOT-1)*KSLOT)?0:sl_next+KSLOT;}while(0)
; template<int THRL> __device__ __forceinline__ void attn_unit128(int qb,const bf16*Qh,const bf16*__restrict__ Kh,const bf16*__restrict__ Vh,bf16*Oh,char*shm){
;     ...
;   int t=1;
;     ...
;   for(;t+5<NT;t+=2){
;     STEP(pB0,pB1,pA0,pA1,t,true,true,true);     WAIT_BAR(3); RESC(); ROT();
;     STEP(pA0,pA1,pB0,pB1,t+1,true,true,true);   WAIT_BAR(3); RESC(); ROT();
.LBB0_373:
	s_waitcnt lgkmcnt(14)
	v_mfma_f32_32x32x16_bf16 v[32:47], v[140:143], v[176:179], v[32:47]
	v_exp_f32_e32 v80, v80
	v_exp_f32_e32 v81, v81
	ds_read_b64_tr_b16 v[104:105], v191 offset:26624
	ds_read_b64_tr_b16 v[106:107], v191 offset:27136
	s_waitcnt lgkmcnt(14)
	v_mfma_f32_32x32x16_bf16 v[48:63], v[140:143], v[172:175], v[48:63]
	v_exp_f32_e32 v82, v82
	v_exp_f32_e32 v83, v83
	ds_read_b64_tr_b16 v[108:109], v191 offset:30720
	ds_read_b64_tr_b16 v[110:111], v191 offset:31232
	s_waitcnt lgkmcnt(14)
	v_mfma_f32_32x32x16_bf16 v[16:31], v[140:143], v[168:171], v[16:31]
	v_exp_f32_e32 v84, v84
	v_exp_f32_e32 v85, v85
	ds_read_b64_tr_b16 v[124:125], v191 offset:34816
	ds_read_b64_tr_b16 v[126:127], v191 offset:35328
	s_waitcnt lgkmcnt(14)
	v_mfma_f32_32x32x16_bf16 v[0:15], v[140:143], v[120:123], v[0:15]
	v_exp_f32_e32 v86, v86
	v_exp_f32_e32 v87, v87
	ds_read_b64_tr_b16 v[120:121], v191 offset:38912
	ds_read_b64_tr_b16 v[122:123], v191 offset:39424
	s_waitcnt lgkmcnt(14)
	v_mfma_f32_32x32x16_bf16 v[32:47], v[136:139], v[116:119], v[32:47]
	v_exp_f32_e32 v88, v88
	v_exp_f32_e32 v89, v89
	ds_read_b64_tr_b16 v[116:117], v191 offset:27648
	ds_read_b64_tr_b16 v[118:119], v191 offset:28160
	s_waitcnt lgkmcnt(14)
	v_mfma_f32_32x32x16_bf16 v[48:63], v[136:139], v[112:115], v[48:63]
	v_exp_f32_e32 v90, v90
	v_exp_f32_e32 v91, v91
	ds_read_b64_tr_b16 v[112:113], v191 offset:31744
	ds_read_b64_tr_b16 v[114:115], v191 offset:32256
	s_waitcnt lgkmcnt(14)
	v_mfma_f32_32x32x16_bf16 v[16:31], v[136:139], v[100:103], v[16:31]
	v_exp_f32_e32 v92, v92
	v_exp_f32_e32 v93, v93
	ds_read_b64_tr_b16 v[100:101], v191 offset:35840
	ds_read_b64_tr_b16 v[102:103], v191 offset:36352
	s_waitcnt lgkmcnt(14)
	v_mfma_f32_32x32x16_bf16 v[0:15], v[136:139], v[96:99], v[0:15]
	v_exp_f32_e32 v94, v94
	v_exp_f32_e32 v95, v95
	ds_read_b64_tr_b16 v[96:97], v191 offset:39936
	ds_read_b64_tr_b16 v[98:99], v191 offset:40448
	v_add_u32_e32 v136, s97, v223
	ds_read_b128 v[168:171], v136
	ds_read_b128 v[160:163], v136 offset:512
	s_waitcnt lgkmcnt(14)
	v_mfma_f32_32x32x16_bf16 v[32:47], v[132:135], v[104:107], v[32:47]
	v_exp_f32_e32 v64, v64
	v_exp_f32_e32 v65, v65
	v_mfma_f32_32x32x16_bf16 v[48:63], v[132:135], v[108:111], v[48:63]
	v_exp_f32_e32 v66, v66
	v_exp_f32_e32 v67, v67
	ds_read_b128 v[172:175], v136 offset:2048
	ds_read_b128 v[156:159], v136 offset:2560
	s_waitcnt lgkmcnt(14)
	v_mfma_f32_32x32x16_bf16 v[16:31], v[132:135], v[124:127], v[16:31]
	v_exp_f32_e32 v68, v68
	v_exp_f32_e32 v69, v69
	s_waitcnt lgkmcnt(12)
	v_mfma_f32_32x32x16_bf16 v[0:15], v[132:135], v[120:123], v[0:15]
	v_exp_f32_e32 v70, v70
	v_exp_f32_e32 v71, v71
	ds_read_b128 v[164:167], v136 offset:4096
	ds_read_b128 v[148:151], v136 offset:4608
	s_waitcnt lgkmcnt(12)
	v_mfma_f32_32x32x16_bf16 v[32:47], v[128:131], v[116:119], v[32:47]
	v_exp_f32_e32 v72, v72
	v_exp_f32_e32 v73, v73
	s_waitcnt lgkmcnt(10)
	v_mfma_f32_32x32x16_bf16 v[48:63], v[128:131], v[112:115], v[48:63]
	v_exp_f32_e32 v74, v74
	v_exp_f32_e32 v75, v75
	ds_read_b128 v[152:155], v136 offset:6144
	ds_read_b128 v[144:147], v136 offset:6656
	s_waitcnt lgkmcnt(10)
	v_mfma_f32_32x32x16_bf16 v[16:31], v[128:131], v[100:103], v[16:31]
	v_exp_f32_e32 v76, v76
	v_exp_f32_e32 v77, v77
	s_waitcnt lgkmcnt(8)
	v_mfma_f32_32x32x16_bf16 v[0:15], v[128:131], v[96:99], v[0:15]
	v_exp_f32_e32 v78, v78
	v_exp_f32_e32 v79, v79
	s_waitcnt vmcnt(3) lgkmcnt(0)
	s_barrier
	s_andn2_b64 vcc, exec, s[20:21]
	s_cbranch_vccnz .LBB0_375
	s_waitcnt lgkmcnt(0)
	ds_read_b128 v[96:99], v187 offset:96
	ds_read_b128 v[100:103], v187 offset:64
	ds_read_b128 v[104:107], v187 offset:32
	ds_read_b128 v[108:111], v187
	s_waitcnt lgkmcnt(3)
	v_pk_mul_f32 v[44:45], v[44:45], v[96:97]
	s_waitcnt lgkmcnt(2)
	v_pk_mul_f32 v[40:41], v[40:41], v[100:101]
	s_waitcnt lgkmcnt(1)
	v_pk_mul_f32 v[36:37], v[36:37], v[104:105]
	v_pk_mul_f32 v[46:47], v[46:47], v[98:99]
	v_pk_mul_f32 v[42:43], v[42:43], v[102:103]
	v_pk_mul_f32 v[38:39], v[38:39], v[106:107]
	s_waitcnt lgkmcnt(0)
	v_pk_mul_f32 v[34:35], v[34:35], v[110:111]
	v_pk_mul_f32 v[32:33], v[32:33], v[108:109]
	v_pk_mul_f32 v[60:61], v[60:61], v[96:97]
	v_pk_mul_f32 v[56:57], v[56:57], v[100:101]
	v_pk_mul_f32 v[52:53], v[52:53], v[104:105]
	v_pk_mul_f32 v[62:63], v[62:63], v[98:99]
	v_pk_mul_f32 v[58:59], v[58:59], v[102:103]
	v_pk_mul_f32 v[54:55], v[54:55], v[106:107]
	v_pk_mul_f32 v[50:51], v[50:51], v[110:111]
	v_pk_mul_f32 v[48:49], v[48:49], v[108:109]
	v_pk_mul_f32 v[28:29], v[28:29], v[96:97]
	v_pk_mul_f32 v[24:25], v[24:25], v[100:101]
	v_pk_mul_f32 v[20:21], v[20:21], v[104:105]
	v_pk_mul_f32 v[30:31], v[30:31], v[98:99]
	v_pk_mul_f32 v[26:27], v[26:27], v[102:103]
	v_pk_mul_f32 v[22:23], v[22:23], v[106:107]
	v_pk_mul_f32 v[18:19], v[18:19], v[110:111]
	v_pk_mul_f32 v[16:17], v[16:17], v[108:109]
	v_pk_mul_f32 v[12:13], v[12:13], v[96:97]
	v_pk_mul_f32 v[8:9], v[8:9], v[100:101]
	v_pk_mul_f32 v[4:5], v[4:5], v[104:105]
	v_pk_mul_f32 v[14:15], v[14:15], v[98:99]
	v_pk_mul_f32 v[10:11], v[10:11], v[102:103]
	v_pk_mul_f32 v[6:7], v[6:7], v[106:107]
	v_pk_mul_f32 v[2:3], v[2:3], v[110:111]
	v_pk_mul_f32 v[0:1], v[0:1], v[108:109]

.LBB0_377:
	v_max_f32_e32 v72, v72, v72
	v_max_f32_e32 v73, 0, v72
	v_exp_f32_e64 v72, -v73
	s_and_saveexec_b64 s[26:27], s[0:1]
	ds_write_b32 v216, v72
	s_or_b64 exec, exec, s[26:27]
	v_add_f32_e32 v220, v220, v73
	v_sub_f32_e32 v96, v96, v73
	v_sub_f32_e32 v97, v97, v73
	v_sub_f32_e32 v98, v98, v73
	v_sub_f32_e32 v99, v99, v73
	v_sub_f32_e32 v100, v100, v73
	v_sub_f32_e32 v101, v101, v73
	v_sub_f32_e32 v102, v102, v73
	v_sub_f32_e32 v103, v103, v73
	v_sub_f32_e32 v104, v104, v73
	v_sub_f32_e32 v105, v105, v73
	v_sub_f32_e32 v106, v106, v73
	v_sub_f32_e32 v107, v107, v73
	v_sub_f32_e32 v108, v108, v73
	v_sub_f32_e32 v109, v109, v73
	v_sub_f32_e32 v110, v110, v73
	v_sub_f32_e32 v111, v111, v73
	v_sub_f32_e32 v112, v112, v73
	v_sub_f32_e32 v113, v113, v73
	v_sub_f32_e32 v114, v114, v73
	v_sub_f32_e32 v115, v115, v73
	v_sub_f32_e32 v116, v116, v73
	v_sub_f32_e32 v117, v117, v73
	v_sub_f32_e32 v118, v118, v73
	v_sub_f32_e32 v119, v119, v73
	v_sub_f32_e32 v120, v120, v73
	v_sub_f32_e32 v121, v121, v73
	v_sub_f32_e32 v122, v122, v73
	v_sub_f32_e32 v123, v123, v73
	v_sub_f32_e32 v124, v124, v73
	v_sub_f32_e32 v125, v125, v73
	v_sub_f32_e32 v126, v126, v73
	v_sub_f32_e32 v127, v127, v73
	v_sub_f32_e32 v192, v192, v73
	v_sub_f32_e32 v193, v193, v73
	v_sub_f32_e32 v194, v194, v73
	v_sub_f32_e32 v195, v195, v73
	v_sub_f32_e32 v196, v196, v73
	v_sub_f32_e32 v197, v197, v73
	v_sub_f32_e32 v198, v198, v73
	v_sub_f32_e32 v199, v199, v73
	v_sub_f32_e32 v200, v200, v73
	v_sub_f32_e32 v201, v201, v73
	v_sub_f32_e32 v202, v202, v73
	v_sub_f32_e32 v203, v203, v73
	v_sub_f32_e32 v204, v204, v73
	v_sub_f32_e32 v205, v205, v73
	v_sub_f32_e32 v206, v206, v73
	v_sub_f32_e32 v207, v207, v73
	v_mul_f32_e32 v190, v190, v72
	s_branch .LBB0_370
.LBB0_380:
	v_max_f32_e32 v104, v104, v104
	v_max_f32_e32 v105, 0, v104
	v_exp_f32_e64 v104, -v105
	s_and_saveexec_b64 s[26:27], s[0:1]
	ds_write_b32 v216, v104
	s_or_b64 exec, exec, s[26:27]
	v_add_f32_e32 v220, v220, v105
	v_sub_f32_e32 v64, v64, v105
	v_sub_f32_e32 v65, v65, v105
	v_sub_f32_e32 v66, v66, v105
	v_sub_f32_e32 v67, v67, v105
	v_sub_f32_e32 v68, v68, v105
	v_sub_f32_e32 v69, v69, v105
	v_sub_f32_e32 v70, v70, v105
	v_sub_f32_e32 v71, v71, v105
	v_sub_f32_e32 v72, v72, v105
	v_sub_f32_e32 v73, v73, v105
	v_sub_f32_e32 v74, v74, v105
	v_sub_f32_e32 v75, v75, v105
	v_sub_f32_e32 v76, v76, v105
	v_sub_f32_e32 v77, v77, v105
	v_sub_f32_e32 v78, v78, v105
	v_sub_f32_e32 v79, v79, v105
	v_sub_f32_e32 v80, v80, v105
	v_sub_f32_e32 v81, v81, v105
	v_sub_f32_e32 v82, v82, v105
	v_sub_f32_e32 v83, v83, v105
	v_sub_f32_e32 v84, v84, v105
	v_sub_f32_e32 v85, v85, v105
	v_sub_f32_e32 v86, v86, v105
	v_sub_f32_e32 v87, v87, v105
	v_sub_f32_e32 v88, v88, v105
	v_sub_f32_e32 v89, v89, v105
	v_sub_f32_e32 v90, v90, v105
	v_sub_f32_e32 v91, v91, v105
	v_sub_f32_e32 v92, v92, v105
	v_sub_f32_e32 v93, v93, v105
	v_sub_f32_e32 v94, v94, v105
	v_sub_f32_e32 v95, v95, v105
	v_sub_f32_e32 v192, v192, v105
	v_sub_f32_e32 v193, v193, v105
	v_sub_f32_e32 v194, v194, v105
	v_sub_f32_e32 v195, v195, v105
	v_sub_f32_e32 v196, v196, v105
	v_sub_f32_e32 v197, v197, v105
	v_sub_f32_e32 v198, v198, v105
	v_sub_f32_e32 v199, v199, v105
	v_sub_f32_e32 v200, v200, v105
	v_sub_f32_e32 v201, v201, v105
	v_sub_f32_e32 v202, v202, v105
	v_sub_f32_e32 v203, v203, v105
	v_sub_f32_e32 v204, v204, v105
	v_sub_f32_e32 v205, v205, v105
	v_sub_f32_e32 v206, v206, v105
	v_sub_f32_e32 v207, v207, v105
	v_mul_f32_e32 v226, v226, v104
	s_branch .LBB0_373

; #define WAIT_BAR(N) asm volatile("s_waitcnt vmcnt(" #N ") lgkmcnt(0)\n\ts_barrier":::"memory")
;   #define RESC() do{ if(resc){ asm volatile("s_waitcnt lgkmcnt(0)":::"memory"); \
;       _Pragma("unroll") for(int d_=0;d_<2;++d_) _Pragma("unroll") for(int r=0;r<16;++r)o[d_][r]*=wsf[crow(r,hi)]; } }while(0)
;   #define ROT() do{sl_prev=sl_cur;sl_cur=sl_next;sl_next=(sl_next==(NSLOT-1)*SLOTB)?0:sl_next+SLOTB;}while(0)
;   #define ENDW(tt) do{ if((tt)+3<NT){WAIT_BAR(2);} else if((tt)+2<NT){WAIT_BAR(1);} else {WAIT_BAR(0);} }while(0)
; #define WAIT_BAR(N) asm volatile("s_waitcnt vmcnt(" #N ") lgkmcnt(0)\n\ts_barrier":::"memory")
;   #define RESC() do{ if(resc){ asm volatile("s_waitcnt lgkmcnt(0)":::"memory"); \
;       _Pragma("unroll") for(int d_=0;d_<4;++d_) _Pragma("unroll") for(int r=0;r<16;++r)o[d_][r]*=wsf[crow(r,hi)]; } }while(0)
;   #define ROT() do{sl_prev=sl_cur;sl_cur=sl_next;sl_next=(sl_next==(NSLOT-1)*KSLOT)?0:sl_next+KSLOT;}while(0)
;   #define ENDW(tt) do{ if((tt)+3<NT){WAIT_BAR(3);} else if((tt)+2<NT){WAIT_BAR(2);} else {WAIT_BAR(0);} }while(0)
; template<int THRL> __device__ __forceinline__ void attn_unit128(int qb,const bf16*Qh,const bf16*__restrict__ Kh,const bf16*__restrict__ Vh,bf16*Oh,char*shm){
;     ...
;   for(;t+5<NT;t+=2){
;     STEP(pB0,pB1,pA0,pA1,t,true,true,true);     WAIT_BAR(3); RESC(); ROT();
;     STEP(pA0,pA1,pB0,pB1,t+1,true,true,true);   WAIT_BAR(3); RESC(); ROT();
;   }
;     ...
;   for(;t+1<NT;t+=2){
;     STEP(pB0,pB1,pA0,pA1,t,(t+3<NT),(t+1<NT),(t+1<NT));       ENDW(t);   RESC(); ROT();
;     STEP(pA0,pA1,pB0,pB1,t+1,(t+4<NT),(t+2<NT),(t+2<NT));     ENDW(t+1); RESC(); ROT();
;   }
;   STEP(pB0,pB1,pA0,pA1,NT-1,false,false,false); RESC();
.LBB0_384:
	v_add_u32_e32 v204, 0xfffed800, v222
	v_bfe_u32 v205, v204, 4, 6
	v_lshrrev_b32_e32 v204, 12, v204
	v_cmp_lt_u32_e64 s[98:99], 5, v204
	v_addc_co_u32_e64 v204, s[98:99], 0, v204, s[98:99]
	v_mul_u32_u24_e32 v204, 0xe00, v204
	v_lshl_add_u32 v189, v205, 2, v204
	v_add_u32_e32 v189, 0x1a800, v189
	ds_read_b32 v192, v189
	ds_read_b32 v193, v189 offset:256
	ds_read_b32 v194, v189 offset:512
	ds_read_b32 v195, v189 offset:768
	ds_read_b32 v196, v189 offset:1024
	ds_read_b32 v197, v189 offset:1280
	ds_read_b32 v198, v189 offset:1536
	ds_read_b32 v199, v189 offset:1792
	ds_read_b32 v200, v189 offset:2048
	ds_read_b32 v201, v189 offset:2304
	ds_read_b32 v202, v189 offset:2560
	ds_read_b32 v203, v189 offset:2816
	ds_read_b32 v206, v189 offset:3072
	ds_read_b32 v207, v189 offset:3328
	s_waitcnt lgkmcnt(0)
	s_add_i32 s72, s19, -3
